# attention QK^T: the 20 K-fragment LDS reads are issued in a burst ahead of the MFMAs with counted lgkmcnt waits (was read-wait-MFMA ten times in series)
# speedup vs baseline: 1.0219x; 1.0067x over previous
.LBB0_752:
	s_or_b64 exec, exec, s[70:71]
	s_ashr_i32 s70, s78, 11
	s_lshl_b32 vcc_lo, s70, 1
	s_and_b32 s69, s78, 0x7f
	s_bfm_b32 s71, vcc_lo, 0
	s_and_b32 s71, s71, s69
	s_bfe_u32 s79, s78, 0x40007
	s_lshr_b32 s72, s69, vcc_lo
	v_add_u32_e32 v2, s68, v138
	s_add_u32 s64, s50, s64
	v_ashrrev_i32_e32 v3, 31, v2
	s_addc_u32 s65, s51, s65
	v_lshlrev_b64 v[2:3], 7, v[2:3]
	v_lshl_add_u64 v[2:3], s[64:65], 0, v[2:3]
	v_mov_b32_e32 v131, v1
	v_lshl_add_u64 v[2:3], v[2:3], 0, v[130:131]
	global_load_dwordx4 v[80:83], v[2:3], off
	global_load_dwordx4 v[84:87], v[2:3], off offset:64
	ds_read_b128 v[216:219], v141 offset:36864
	ds_read_b128 v[220:223], v141 offset:36928
	ds_read_b128 v[224:227], v142 offset:36864
	ds_read_b128 v[228:231], v142 offset:36928
	ds_read_b128 v[232:235], v143 offset:36864
	ds_read_b128 v[236:239], v143 offset:36928
	ds_read_b128 v[240:243], v144 offset:36864
	ds_read_b128 v[244:247], v144 offset:36928
	ds_read_b128 v[182:185], v145 offset:36864
	ds_read_b128 v[186:189], v145 offset:36928
	ds_read_b128 v[190:193], v146 offset:36864
	ds_read_b128 v[194:197], v146 offset:36928
	ds_read_b128 v[160:163], v147 offset:36864
	ds_read_b128 v[198:201], v147 offset:36928
	s_waitcnt vmcnt(13) lgkmcnt(13)
	v_mfma_f32_16x16x32_bf16 v[152:155], v[216:219], v[88:91], 0
	v_lshl_add_u32 v0, s72, 7, v138
	s_cmp_lg_u32 s72, 0
	s_cselect_b32 s100, 0, 0x80
	v_lshrrev_b32_e32 v178, 6, v202
	v_and_b32_e32 v179, 15, v202
	v_lshl_or_b32 v178, v178, 4, v179
	v_lshrrev_b32_e32 v179, 7, v202
	v_bfe_u32 v180, v202, 4, 2
	v_lshlrev_b32_e32 v180, 2, v180
	v_lshl_add_u32 v179, v179, 5, v180
	v_max_u32_e32 v180, s100, v178
	v_sub_u32_e32 v175, v179, v180
	v_sub_u32_e32 v176, v178, v180
	v_add_u32_e32 v176, 0x81, v176
	v_lshlrev_b32_e32 v0, vcc_lo, v0
	s_waitcnt vmcnt(12) lgkmcnt(12)
	v_mfma_f32_16x16x32_bf16 v[152:155], v[220:223], v[92:95], v[152:155]
	ds_read_b128 v[216:219], v148 offset:36864
	ds_read_b128 v[220:223], v148 offset:36928
	s_waitcnt lgkmcnt(13)
	v_mfma_f32_16x16x32_bf16 v[124:127], v[224:227], v[88:91], 0
	s_waitcnt lgkmcnt(12)
	v_mfma_f32_16x16x32_bf16 v[124:127], v[228:231], v[92:95], v[124:127]
	ds_read_b128 v[224:227], v149 offset:36864
	ds_read_b128 v[228:231], v149 offset:36928
	s_waitcnt lgkmcnt(13)
	v_mfma_f32_16x16x32_bf16 v[120:123], v[232:235], v[88:91], 0
	s_waitcnt lgkmcnt(12)
	v_mfma_f32_16x16x32_bf16 v[120:123], v[236:239], v[92:95], v[120:123]
	ds_read_b128 v[232:235], v150 offset:36864
	ds_read_b128 v[236:239], v150 offset:36928
	s_waitcnt lgkmcnt(13)
	v_mfma_f32_16x16x32_bf16 v[116:119], v[240:243], v[88:91], 0
	s_waitcnt lgkmcnt(12)
	v_mfma_f32_16x16x32_bf16 v[116:119], v[244:247], v[92:95], v[116:119]
	s_waitcnt lgkmcnt(11)
	v_mfma_f32_16x16x32_bf16 v[112:115], v[182:185], v[88:91], 0
	s_waitcnt lgkmcnt(10)
	v_mfma_f32_16x16x32_bf16 v[112:115], v[186:189], v[92:95], v[112:115]
	s_waitcnt lgkmcnt(9)
	v_mfma_f32_16x16x32_bf16 v[108:111], v[190:193], v[88:91], 0
	s_waitcnt lgkmcnt(8)
	v_mfma_f32_16x16x32_bf16 v[108:111], v[194:197], v[92:95], v[108:111]
	s_waitcnt lgkmcnt(7)
	v_mfma_f32_16x16x32_bf16 v[104:107], v[160:163], v[88:91], 0
	s_waitcnt lgkmcnt(6)
	v_mfma_f32_16x16x32_bf16 v[104:107], v[198:201], v[92:95], v[104:107]
	s_waitcnt lgkmcnt(5)
	v_mfma_f32_16x16x32_bf16 v[100:103], v[216:219], v[88:91], 0
	s_waitcnt lgkmcnt(4)
	v_mfma_f32_16x16x32_bf16 v[100:103], v[220:223], v[92:95], v[100:103]
	s_waitcnt lgkmcnt(3)
	v_mfma_f32_16x16x32_bf16 v[96:99], v[224:227], v[88:91], 0
	s_waitcnt lgkmcnt(2)
	v_mfma_f32_16x16x32_bf16 v[96:99], v[228:231], v[92:95], v[96:99]
	s_waitcnt lgkmcnt(1)
	v_mfma_f32_16x16x32_bf16 v[88:91], v[232:235], v[88:91], 0
	s_waitcnt lgkmcnt(0)
	v_mfma_f32_16x16x32_bf16 v[88:91], v[236:239], v[92:95], v[88:91]
	s_mov_b32 s68, 0xff61b1e6
	v_add_u32_e32 v177, 0, v175
	v_cmp_lt_u32_e32 vcc, v177, v176
	s_nop 1
	v_cndmask_b32_e32 v3, v213, v152, vcc
	v_add_u32_e32 v177, 1, v175
	v_cmp_lt_u32_e32 vcc, v177, v176
	s_nop 1
	v_cndmask_b32_e32 v2, v213, v153, vcc
	v_max3_f32 v94, v3, s68, v2
	v_add_u32_e32 v177, 2, v175
	v_cmp_lt_u32_e32 vcc, v177, v176
	s_nop 1
	v_cndmask_b32_e32 v92, v213, v154, vcc
	v_add_u32_e32 v177, 3, v175
	v_cmp_lt_u32_e32 vcc, v177, v176
	s_nop 1
	v_cndmask_b32_e32 v93, v213, v155, vcc
	v_add_u32_e32 v177, 16, v175
	v_cmp_lt_u32_e32 vcc, v177, v176
	s_nop 1
	v_cndmask_b32_e32 v95, v213, v124, vcc
	v_max3_f32 v129, v94, v92, v93
	v_add_u32_e32 v177, 17, v175
	v_cmp_lt_u32_e32 vcc, v177, v176
	s_nop 1
	v_cndmask_b32_e32 v94, v213, v125, vcc
	v_add_u32_e32 v177, 18, v175
	v_cmp_lt_u32_e32 vcc, v177, v176
	s_nop 1
	v_cndmask_b32_e32 v124, v213, v126, vcc
	v_add_u32_e32 v177, 19, v175
	v_cmp_lt_u32_e32 vcc, v177, v176
	s_nop 1
	v_cndmask_b32_e32 v125, v213, v127, vcc
	v_add_u32_e32 v177, 32, v175
	v_cmp_lt_u32_e32 vcc, v177, v176
	s_nop 1
	v_cndmask_b32_e32 v126, v213, v120, vcc
	v_add_u32_e32 v177, 33, v175
	v_cmp_lt_u32_e32 vcc, v177, v176
	s_nop 1
	v_cndmask_b32_e32 v120, v213, v121, vcc
	v_add_u32_e32 v177, 34, v175
	v_cmp_lt_u32_e32 vcc, v177, v176
	s_nop 1
	v_cndmask_b32_e32 v121, v213, v122, vcc
	v_add_u32_e32 v177, 35, v175
	v_cmp_lt_u32_e32 vcc, v177, v176
	s_nop 1
	v_cndmask_b32_e32 v122, v213, v123, vcc
	v_add_u32_e32 v177, 48, v175
	v_cmp_lt_u32_e32 vcc, v177, v176
	s_nop 1
	v_cndmask_b32_e32 v123, v213, v116, vcc
	v_add_u32_e32 v177, 49, v175
	v_cmp_lt_u32_e32 vcc, v177, v176
	s_nop 1
	v_cndmask_b32_e32 v116, v213, v117, vcc
	v_add_u32_e32 v177, 50, v175
	v_cmp_lt_u32_e32 vcc, v177, v176
	s_nop 1
	v_cndmask_b32_e32 v117, v213, v118, vcc
	v_add_u32_e32 v177, 51, v175
	v_cmp_lt_u32_e32 vcc, v177, v176
	s_nop 1
	v_cndmask_b32_e32 v118, v213, v119, vcc
	v_add_u32_e32 v177, 64, v175
	v_cmp_lt_u32_e32 vcc, v177, v176
	s_nop 1
	v_cndmask_b32_e32 v119, v213, v112, vcc
	v_add_u32_e32 v177, 0x41, v175
	v_cmp_lt_u32_e32 vcc, v177, v176
	s_nop 1
	v_cndmask_b32_e32 v112, v213, v113, vcc
	v_add_u32_e32 v177, 0x42, v175
	v_cmp_lt_u32_e32 vcc, v177, v176
	s_nop 1
	v_cndmask_b32_e32 v113, v213, v114, vcc
	v_add_u32_e32 v177, 0x43, v175
	v_cmp_lt_u32_e32 vcc, v177, v176
	s_nop 1
	v_cndmask_b32_e32 v114, v213, v115, vcc
	v_add_u32_e32 v177, 0x50, v175
	v_cmp_lt_u32_e32 vcc, v177, v176
	s_nop 1
	v_cndmask_b32_e32 v115, v213, v108, vcc
	v_add_u32_e32 v177, 0x51, v175
	v_cmp_lt_u32_e32 vcc, v177, v176
	s_nop 1
	v_cndmask_b32_e32 v108, v213, v109, vcc
	v_add_u32_e32 v177, 0x52, v175
	v_cmp_lt_u32_e32 vcc, v177, v176
	s_nop 1
	v_cndmask_b32_e32 v109, v213, v110, vcc
	v_add_u32_e32 v177, 0x53, v175
	v_cmp_lt_u32_e32 vcc, v177, v176
	s_nop 1
	v_cndmask_b32_e32 v110, v213, v111, vcc
	v_max3_f32 v129, v129, v95, v94
	v_add_u32_e32 v177, 0x60, v175
	v_cmp_lt_u32_e32 vcc, v177, v176
	s_nop 1
	v_cndmask_b32_e32 v111, v213, v104, vcc
	v_max3_f32 v127, v129, v124, v125
	v_max3_f32 v127, v127, v126, v120
	v_add_u32_e32 v177, 0x61, v175
	v_cmp_lt_u32_e32 vcc, v177, v176
	s_nop 1
	v_cndmask_b32_e32 v104, v213, v105, vcc
	v_max3_f32 v127, v127, v121, v122
	v_max3_f32 v127, v127, v123, v116
	v_max3_f32 v127, v127, v117, v118
	v_add_u32_e32 v177, 0x62, v175
	v_cmp_lt_u32_e32 vcc, v177, v176
	s_nop 1
	v_cndmask_b32_e32 v105, v213, v106, vcc
	v_max3_f32 v127, v127, v119, v112
	v_max3_f32 v127, v127, v113, v114
	v_max3_f32 v127, v127, v115, v108
	v_add_u32_e32 v177, 0x63, v175
	v_cmp_lt_u32_e32 vcc, v177, v176
	s_nop 1
	v_cndmask_b32_e32 v107, v213, v107, vcc
	v_max3_f32 v127, v127, v109, v110
	v_max3_f32 v127, v127, v111, v104
	v_max3_f32 v106, v127, v105, v107
	v_add_u32_e32 v177, 0x70, v175
	v_cmp_lt_u32_e32 vcc, v177, v176
	s_nop 1
	v_cndmask_b32_e32 v127, v213, v100, vcc
	v_add_u32_e32 v177, 0x71, v175
	v_cmp_lt_u32_e32 vcc, v177, v176
	s_nop 1
	v_cndmask_b32_e32 v100, v213, v101, vcc
	v_add_u32_e32 v177, 0x72, v175
	v_cmp_lt_u32_e32 vcc, v177, v176
	s_nop 1
	v_cndmask_b32_e32 v101, v213, v102, vcc
	v_add_u32_e32 v177, 0x73, v175
	v_cmp_lt_u32_e32 vcc, v177, v176
	s_nop 1
	v_cndmask_b32_e32 v102, v213, v103, vcc
	v_add_u32_e32 v177, 0x80, v175
	v_cmp_lt_u32_e32 vcc, v177, v176
	s_nop 1
	v_cndmask_b32_e32 v103, v213, v96, vcc
	v_add_u32_e32 v177, 0x81, v175
	v_cmp_lt_u32_e32 vcc, v177, v176
	s_nop 1
	v_cndmask_b32_e32 v96, v213, v97, vcc
	v_add_u32_e32 v177, 0x82, v175
	v_cmp_lt_u32_e32 vcc, v177, v176
	s_nop 1
	v_cndmask_b32_e32 v97, v213, v98, vcc
	v_add_u32_e32 v177, 0x83, v175
	v_cmp_lt_u32_e32 vcc, v177, v176
	s_nop 1
	v_cndmask_b32_e32 v99, v213, v99, vcc
	v_add_u32_e32 v177, 0x90, v175
	v_cmp_lt_u32_e32 vcc, v177, v176
	s_nop 1
	v_cndmask_b32_e32 v129, v213, v88, vcc
	v_max3_f32 v106, v106, v127, v100
	v_add_u32_e32 v177, 0x91, v175
	v_cmp_lt_u32_e32 vcc, v177, v176
	s_nop 1
	v_cndmask_b32_e32 v98, v213, v89, vcc
	v_max3_f32 v106, v106, v101, v102
	v_max3_f32 v106, v106, v103, v96
	v_max3_f32 v106, v106, v97, v99
	v_add_u32_e32 v177, 0x92, v175
	v_cmp_lt_u32_e32 vcc, v177, v176
	s_nop 1
	v_cndmask_b32_e32 v90, v213, v90, vcc
	v_max3_f32 v88, v106, v129, v98
	v_add_u32_e32 v177, 0x93, v175
	v_cmp_lt_u32_e32 vcc, v177, v176
	s_nop 1
	v_cndmask_b32_e32 v89, v213, v91, vcc
	v_cmp_lt_i32_e32 vcc, v209, v210
	v_max3_f32 v91, v88, v90, v89
	s_nop 0
	v_cndmask_b32_e32 v88, v208, v209, vcc
	v_lshlrev_b32_e32 v88, 2, v88
	ds_bpermute_b32 v106, v88, v91
	v_cmp_lt_i32_e32 vcc, v211, v210
	s_waitcnt lgkmcnt(0)
	v_max_f32_e32 v106, v106, v106
	v_max_f32_e32 v91, v91, v106
	v_cndmask_b32_e32 v106, v208, v211, vcc
	v_lshlrev_b32_e32 v131, 2, v106
	ds_bpermute_b32 v106, v131, v91
	s_waitcnt lgkmcnt(0)
	v_max_f32_e32 v106, v106, v106
	v_max_f32_e32 v106, v91, v106
	v_sub_f32_e32 v3, v3, v106
	v_mul_f32_e32 v3, 0x3fb8aa3b, v3
	v_sub_f32_e32 v2, v2, v106
	v_exp_f32_e32 v3, v3
	v_mul_f32_e32 v2, 0x3fb8aa3b, v2
	v_exp_f32_e32 v135, v2
	v_sub_f32_e32 v94, v94, v106
	v_add_f32_e32 v91, 0, v3
	v_mul_f32_e32 v94, 0x3fb8aa3b, v94
	v_add_f32_e32 v2, v135, v91
	v_sub_f32_e32 v91, v92, v106
	v_mul_f32_e32 v91, 0x3fb8aa3b, v91
	v_sub_f32_e32 v92, v93, v106
	v_exp_f32_e32 v91, v91
	v_mul_f32_e32 v92, 0x3fb8aa3b, v92
	v_sub_f32_e32 v93, v95, v106
	v_exp_f32_e32 v92, v92
	v_mul_f32_e32 v93, 0x3fb8aa3b, v93
	v_exp_f32_e32 v93, v93
	v_sub_f32_e32 v95, v124, v106
	v_exp_f32_e32 v94, v94
	v_mul_f32_e32 v95, 0x3fb8aa3b, v95
	v_sub_f32_e32 v124, v125, v106
	v_add_f32_e32 v2, v91, v2
	v_exp_f32_e32 v95, v95
	v_mul_f32_e32 v124, 0x3fb8aa3b, v124
	v_sub_f32_e32 v125, v126, v106
	v_add_f32_e32 v2, v92, v2
	v_exp_f32_e32 v124, v124
	v_mul_f32_e32 v125, 0x3fb8aa3b, v125
	v_sub_f32_e32 v120, v120, v106
	v_add_f32_e32 v2, v93, v2
	v_exp_f32_e32 v125, v125
	v_mul_f32_e32 v120, 0x3fb8aa3b, v120
	v_sub_f32_e32 v121, v121, v106
	v_add_f32_e32 v2, v94, v2
	v_exp_f32_e32 v120, v120
	v_mul_f32_e32 v121, 0x3fb8aa3b, v121
	v_sub_f32_e32 v122, v122, v106
	v_add_f32_e32 v2, v95, v2
	v_exp_f32_e32 v121, v121
	v_mul_f32_e32 v122, 0x3fb8aa3b, v122
	v_sub_f32_e32 v123, v123, v106
	v_add_f32_e32 v2, v124, v2
	v_exp_f32_e32 v122, v122
	v_mul_f32_e32 v123, 0x3fb8aa3b, v123
	v_sub_f32_e32 v116, v116, v106
	v_add_f32_e32 v2, v125, v2
	v_exp_f32_e32 v123, v123
	v_mul_f32_e32 v116, 0x3fb8aa3b, v116
	v_sub_f32_e32 v117, v117, v106
	v_sub_f32_e32 v112, v112, v106
	v_add_f32_e32 v2, v120, v2
	v_exp_f32_e32 v116, v116
	v_mul_f32_e32 v117, 0x3fb8aa3b, v117
	v_sub_f32_e32 v118, v118, v106
	v_mul_f32_e32 v112, 0x3fb8aa3b, v112
	v_add_f32_e32 v2, v121, v2
	v_exp_f32_e32 v117, v117
	v_mul_f32_e32 v118, 0x3fb8aa3b, v118
	v_sub_f32_e32 v119, v119, v106
	v_exp_f32_e32 v126, v112
	v_sub_f32_e32 v112, v113, v106
	v_add_f32_e32 v2, v122, v2
	v_exp_f32_e32 v118, v118
	v_mul_f32_e32 v119, 0x3fb8aa3b, v119
	v_mul_f32_e32 v112, 0x3fb8aa3b, v112
	v_add_f32_e32 v2, v123, v2
	v_exp_f32_e32 v119, v119
	v_exp_f32_e32 v152, v112
	v_sub_f32_e32 v112, v114, v106
	v_sub_f32_e32 v108, v108, v106
	v_add_f32_e32 v2, v116, v2
	v_mul_f32_e32 v112, 0x3fb8aa3b, v112
	v_mul_f32_e32 v108, 0x3fb8aa3b, v108
	v_add_f32_e32 v2, v117, v2
	v_exp_f32_e32 v153, v112
	v_sub_f32_e32 v112, v115, v106
	v_exp_f32_e32 v155, v108
	v_sub_f32_e32 v108, v109, v106
	v_add_f32_e32 v2, v118, v2
	v_mul_f32_e32 v112, 0x3fb8aa3b, v112
	v_mul_f32_e32 v108, 0x3fb8aa3b, v108
	v_add_f32_e32 v2, v119, v2
	v_exp_f32_e32 v154, v112
	v_exp_f32_e32 v160, v108
	v_sub_f32_e32 v108, v110, v106
	v_add_f32_e32 v2, v126, v2
	v_mul_f32_e32 v108, 0x3fb8aa3b, v108
	v_add_f32_e32 v2, v152, v2
	v_exp_f32_e32 v161, v108
	v_sub_f32_e32 v108, v111, v106
	v_add_f32_e32 v2, v153, v2
	v_mul_f32_e32 v108, 0x3fb8aa3b, v108
	v_sub_f32_e32 v104, v104, v106
	v_add_f32_e32 v2, v154, v2
	v_exp_f32_e32 v162, v108
	v_mul_f32_e32 v104, 0x3fb8aa3b, v104
	v_sub_f32_e32 v105, v105, v106
	v_sub_f32_e32 v100, v100, v106
	v_add_f32_e32 v2, v155, v2
	v_exp_f32_e32 v104, v104
	v_mul_f32_e32 v105, 0x3fb8aa3b, v105
	v_sub_f32_e32 v107, v107, v106
	v_mul_f32_e32 v100, 0x3fb8aa3b, v100
	v_add_f32_e32 v2, v160, v2
	v_exp_f32_e32 v105, v105
	v_mul_f32_e32 v107, 0x3fb8aa3b, v107
	v_sub_f32_e32 v108, v127, v106
	v_exp_f32_e32 v163, v100
	v_sub_f32_e32 v100, v101, v106
	v_add_f32_e32 v2, v161, v2
	v_exp_f32_e32 v107, v107
	v_mul_f32_e32 v108, 0x3fb8aa3b, v108
	v_mul_f32_e32 v100, 0x3fb8aa3b, v100
	v_sub_f32_e32 v96, v96, v106
	v_add_f32_e32 v2, v162, v2
	v_exp_f32_e32 v127, v108
	v_exp_f32_e32 v165, v100
	v_sub_f32_e32 v100, v102, v106
	v_mul_f32_e32 v96, 0x3fb8aa3b, v96
	v_add_f32_e32 v2, v104, v2
	v_mul_f32_e32 v100, 0x3fb8aa3b, v100
	v_exp_f32_e32 v168, v96
	v_sub_f32_e32 v96, v97, v106
	v_add_f32_e32 v2, v105, v2
	v_exp_f32_e32 v166, v100
	v_sub_f32_e32 v100, v103, v106
	v_mul_f32_e32 v96, 0x3fb8aa3b, v96
	v_add_f32_e32 v2, v107, v2
	v_mul_f32_e32 v100, 0x3fb8aa3b, v100
	v_exp_f32_e32 v169, v96
	v_sub_f32_e32 v96, v99, v106
	v_add_f32_e32 v2, v127, v2
	v_exp_f32_e32 v167, v100
	v_mul_f32_e32 v96, 0x3fb8aa3b, v96
	v_add_f32_e32 v2, v163, v2
	v_exp_f32_e32 v170, v96
	v_sub_f32_e32 v96, v129, v106
	v_add_f32_e32 v2, v165, v2
	v_mul_f32_e32 v96, 0x3fb8aa3b, v96
	v_add_f32_e32 v2, v166, v2
	v_exp_f32_e32 v129, v96
	v_sub_f32_e32 v96, v98, v106
	v_add_f32_e32 v2, v167, v2
	v_mul_f32_e32 v96, 0x3fb8aa3b, v96
	v_sub_f32_e32 v90, v90, v106
	v_add_f32_e32 v2, v168, v2
	v_exp_f32_e32 v171, v96
	v_mul_f32_e32 v90, 0x3fb8aa3b, v90
	v_sub_f32_e32 v89, v89, v106
	v_add_f32_e32 v2, v169, v2
	v_exp_f32_e32 v172, v90
	v_mul_f32_e32 v89, 0x3fb8aa3b, v89
	v_add_f32_e32 v2, v170, v2
	v_exp_f32_e32 v173, v89
	v_add_f32_e32 v2, v129, v2
	v_add_f32_e32 v2, v171, v2
	v_add_f32_e32 v2, v172, v2
	v_add_f32_e32 v2, v173, v2
	ds_bpermute_b32 v88, v88, v2
	v_cvt_pk_bf16_f32 v89, v91, v92
	v_cvt_pk_bf16_f32 v90, v93, v94
	v_cvt_pk_bf16_f32 v91, v95, v124
	ds_read2_b64 v[92:95], v151 offset1:4
	s_waitcnt lgkmcnt(1)
	v_add_f32_e32 v174, v2, v88
	v_add_u32_e32 v2, s71, v0
	v_cvt_pk_bf16_f32 v88, v3, v135
	v_add_u32_e32 v0, 0x2000, v151
	v_add_u32_e32 v3, 0x4000, v151
	v_add_u32_e32 v124, 0x6000, v151
	ds_read2_b64 v[96:99], v0 offset0:68 offset1:72
	ds_read2_b64 v[100:103], v3 offset0:136 offset1:140
	ds_read2_b64 v[108:111], v124 offset0:204 offset1:208
	ds_read2_b64 v[112:115], v151 offset0:8 offset1:12
	s_waitcnt lgkmcnt(4)
	v_mfma_f32_16x16x32_bf16 v[92:95], v[92:95], v[88:91], 0
	ds_bpermute_b32 v131, v131, v174
	s_ashr_i32 s71, s70, 31
	v_mov_b32_e32 v135, v1
	s_waitcnt lgkmcnt(4)
	v_mfma_f32_16x16x32_bf16 v[96:99], v[96:99], v[88:91], 0
	s_waitcnt lgkmcnt(3)
	v_mfma_f32_16x16x32_bf16 v[100:103], v[100:103], v[88:91], 0
	s_waitcnt lgkmcnt(2)
	v_mfma_f32_16x16x32_bf16 v[88:91], v[108:111], v[88:91], 0
	v_cvt_pk_bf16_f32 v108, v125, v120
	v_cvt_pk_bf16_f32 v109, v121, v122
	v_cvt_pk_bf16_f32 v110, v123, v116
	v_cvt_pk_bf16_f32 v111, v117, v118
	s_waitcnt lgkmcnt(1)
	s_nop 0
	v_mfma_f32_16x16x32_bf16 v[92:95], v[112:115], v[108:111], v[92:95]
	ds_read2_b64 v[112:115], v0 offset0:76 offset1:80
	s_waitcnt lgkmcnt(0)
	v_mfma_f32_16x16x32_bf16 v[96:99], v[112:115], v[108:111], v[96:99]
	ds_read2_b64 v[112:115], v3 offset0:144 offset1:148
	s_waitcnt lgkmcnt(0)
	v_mfma_f32_16x16x32_bf16 v[100:103], v[112:115], v[108:111], v[100:103]
	ds_read2_b64 v[112:115], v124 offset0:212 offset1:216
	s_waitcnt lgkmcnt(0)
	v_mfma_f32_16x16x32_bf16 v[88:91], v[112:115], v[108:111], v[88:91]
	ds_read2_b64 v[112:115], v151 offset0:16 offset1:20
	v_cvt_pk_bf16_f32 v108, v119, v126
	v_cvt_pk_bf16_f32 v109, v152, v153
	v_cvt_pk_bf16_f32 v110, v154, v155
	v_cvt_pk_bf16_f32 v111, v160, v161
	s_waitcnt lgkmcnt(0)
	s_nop 0
	v_mfma_f32_16x16x32_bf16 v[92:95], v[112:115], v[108:111], v[92:95]
	ds_read2_b64 v[112:115], v0 offset0:84 offset1:88
	s_waitcnt lgkmcnt(0)
	v_mfma_f32_16x16x32_bf16 v[96:99], v[112:115], v[108:111], v[96:99]
	ds_read2_b64 v[112:115], v3 offset0:152 offset1:156
	s_waitcnt lgkmcnt(0)
	v_mfma_f32_16x16x32_bf16 v[100:103], v[112:115], v[108:111], v[100:103]
	ds_read2_b64 v[112:115], v124 offset0:220 offset1:224
	s_waitcnt lgkmcnt(0)
	v_mfma_f32_16x16x32_bf16 v[88:91], v[112:115], v[108:111], v[88:91]
	ds_read2_b64 v[112:115], v151 offset0:24 offset1:28
	v_cvt_pk_bf16_f32 v108, v162, v104
	v_cvt_pk_bf16_f32 v109, v105, v107
	v_cvt_pk_bf16_f32 v110, v127, v163
	v_cvt_pk_bf16_f32 v111, v165, v166
	v_add_f32_e32 v107, v174, v131
	s_waitcnt lgkmcnt(0)
	v_mfma_f32_16x16x32_bf16 v[92:95], v[112:115], v[108:111], v[92:95]
	ds_read2_b64 v[112:115], v0 offset0:92 offset1:96
	s_waitcnt lgkmcnt(0)
	v_mfma_f32_16x16x32_bf16 v[96:99], v[112:115], v[108:111], v[96:99]
	ds_read2_b64 v[112:115], v3 offset0:160 offset1:164
	s_waitcnt lgkmcnt(0)
	v_mfma_f32_16x16x32_bf16 v[112:115], v[112:115], v[108:111], v[100:103]
	s_nop 2
	ds_read2_b64 v[100:103], v124 offset0:228 offset1:232
	s_waitcnt lgkmcnt(0)
	v_mfma_f32_16x16x32_bf16 v[88:91], v[100:103], v[108:111], v[88:91]
	ds_read2_b64 v[100:103], v151 offset0:32 offset1:36
	v_cvt_pk_bf16_f32 v108, v167, v168
	v_cvt_pk_bf16_f32 v109, v169, v170
	v_cvt_pk_bf16_f32 v110, v129, v171
	v_cvt_pk_bf16_f32 v111, v172, v173
	s_waitcnt lgkmcnt(0)
	s_nop 0
	v_mfma_f32_16x16x32_bf16 v[100:103], v[100:103], v[108:111], v[92:95]
	s_nop 2
	ds_read2_b64 v[92:95], v0 offset0:100 offset1:104
	v_div_scale_f32 v0, s[64:65], v107, v107, 1.0
	s_waitcnt lgkmcnt(0)
	v_mfma_f32_16x16x32_bf16 v[96:99], v[92:95], v[108:111], v[96:99]
	ds_read2_b64 v[92:95], v3 offset0:168 offset1:172
	v_rcp_f32_e32 v3, v0
	s_lshl_b64 s[64:65], s[70:71], 25
	s_waitcnt lgkmcnt(0)
	v_mfma_f32_16x16x32_bf16 v[92:95], v[92:95], v[108:111], v[112:115]
	s_nop 2
	ds_read2_b64 v[112:115], v124 offset0:236 offset1:240
	v_fma_f32 v104, -v0, v3, 1.0
	v_fmac_f32_e32 v3, v104, v3
	v_div_scale_f32 v104, vcc, 1.0, v107, 1.0
	v_mul_f32_e32 v105, v104, v3
	s_waitcnt lgkmcnt(0)
	v_mfma_f32_16x16x32_bf16 v[88:91], v[112:115], v[108:111], v[88:91]
	v_fma_f32 v108, -v0, v105, v104
	v_fmac_f32_e32 v105, v108, v3
	v_fma_f32 v0, -v0, v105, v104
	v_div_fmas_f32 v0, v0, v3, v105
	s_add_u32 s64, s52, s64
	v_ashrrev_i32_e32 v3, 31, v2
	s_addc_u32 s65, s53, s65
	v_lshlrev_b64 v[104:105], 11, v[2:3]
	v_div_fixup_f32 v0, v0, v107, 1.0
	v_lshl_add_u64 v[104:105], s[64:65], 0, v[104:105]
	s_lshl_b32 s72, s79, 7
	v_lshl_add_u64 v[104:105], v[104:105], 0, s[72:73]
	v_pk_mul_f32 v[100:101], v[0:1], v[100:101] op_sel_hi:[0,1]
	v_pk_mul_f32 v[102:103], v[0:1], v[102:103] op_sel_hi:[0,1]
	v_pk_mul_f32 v[96:97], v[0:1], v[96:97] op_sel_hi:[0,1]
	v_pk_mul_f32 v[98:99], v[0:1], v[98:99] op_sel_hi:[0,1]
	v_pk_mul_f32 v[92:93], v[0:1], v[92:93] op_sel_hi:[0,1]
	v_pk_mul_f32 v[94:95], v[0:1], v[94:95] op_sel_hi:[0,1]
	v_pk_mul_f32 v[88:89], v[0:1], v[88:89] op_sel_hi:[0,1]
	v_pk_mul_f32 v[90:91], v[0:1], v[90:91] op_sel_hi:[0,1]
	v_lshl_add_u64 v[104:105], v[104:105], 0, v[134:135]
	v_cvt_pk_bf16_f32 v100, v100, v101
	v_cvt_pk_bf16_f32 v101, v102, v103
	v_cvt_pk_bf16_f32 v96, v96, v97
	v_cvt_pk_bf16_f32 v97, v98, v99
	v_cvt_pk_bf16_f32 v92, v92, v93
	v_cvt_pk_bf16_f32 v93, v94, v95
	v_cvt_pk_bf16_f32 v88, v88, v89
	v_cvt_pk_bf16_f32 v89, v90, v91
	global_store_dwordx2 v[104:105], v[100:101], off
	global_store_dwordx2 v[104:105], v[96:97], off offset:32
	global_store_dwordx2 v[104:105], v[92:93], off offset:64
	global_store_dwordx2 v[104:105], v[88:89], off offset:96
	s_mov_b64 s[64:65], exec
	v_readlane_b32 s68, v255, 11
	v_readlane_b32 s69, v255, 12
	s_and_b64 s[68:69], s[64:65], s[68:69]
	s_mov_b64 exec, s[68:69]
	s_cbranch_execz .LBB0_749
	s_mov_b32 s68, 0x800000
	v_cmp_gt_f32_e32 vcc, s68, v107
	s_mov_b32 s68, 0x3f317217
	v_lshlrev_b64 v[2:3], 6, v[2:3]
	v_cndmask_b32_e64 v0, 0, 32, vcc
	v_ldexp_f32 v0, v107, v0
	v_log_f32_e32 v0, v0
	v_cndmask_b32_e32 v88, 0, v212, vcc
	v_mul_f32_e32 v89, 0x3f317217, v0
	v_fma_f32 v89, v0, s68, -v89
	s_mov_b32 s68, 0x7f800000
	v_fmac_f32_e32 v89, 0x3377d1cf, v0
	v_cmp_lt_f32_e64 vcc, |v0|, s68
	s_lshl_b64 s[68:69], s[70:71], 20
	v_fmac_f32_e32 v89, 0x3f317217, v0
	s_add_u32 s68, s55, s68
	v_readlane_b32 s70, v254, 44
	v_cndmask_b32_e32 v0, v0, v89, vcc
	s_addc_u32 s69, s70, s69
	v_sub_f32_e32 v0, v0, v88
	v_lshl_add_u64 v[2:3], s[68:69], 0, v[2:3]
	s_lshl_b32 s72, s79, 2
	v_add_f32_e32 v0, v106, v0
	v_lshl_add_u64 v[2:3], v[2:3], 0, s[72:73]
	global_store_dword v[2:3], v0, off
	s_branch .LBB0_749
